# P7 epilogue (x1 = x + acc, bf16 copy, row sum of squares): 16 x-loads in flight per wave instead of a 32-step ladder; 8 row reductions shuffled together
# speedup vs baseline: 1.0139x; 1.0139x over previous
.LBB0_508:
	v_lshl_add_u32 v142, s10, 8, v144
	v_lshl_or_b32 v140, s62, 8, v146
	v_lshl_add_u32 v150, v142, 10, v140
	v_lshlrev_b32_e32 v154, 2, v150
	v_lshlrev_b32_e32 v165, 1, v150
	v_add_u32_e32 v155, 0x10000, v154
	v_add_u32_e32 v166, 0x8000, v165
	v_add_u32_e32 v156, 0x20000, v154
	v_add_u32_e32 v167, 0x10000, v165
	v_add_u32_e32 v157, 0x30000, v154
	v_add_u32_e32 v168, 0x18000, v165
	v_add_u32_e32 v158, 0x80000, v154
	v_add_u32_e32 v169, 0x40000, v165
	v_add_u32_e32 v159, 0x90000, v154
	v_add_u32_e32 v170, 0x48000, v165
	v_add_u32_e32 v160, 0xa0000, v154
	v_add_u32_e32 v171, 0x50000, v165
	v_add_u32_e32 v161, 0xb0000, v154
	v_add_u32_e32 v172, 0x58000, v165
	v_cmp_lt_i32_e32 vcc, v162, v163
	s_nop 1
	v_cndmask_b32_e32 v173, v181, v162, vcc
	v_lshlrev_b32_e32 v173, 2, v173
	v_cmp_lt_i32_e32 vcc, v164, v163
	s_nop 1
	v_cndmask_b32_e32 v174, v181, v164, vcc
	v_lshlrev_b32_e32 v174, 2, v174
	s_lshl_b32 s48, s62, 4
	s_lshl_b32 s49, s55, 2
	s_add_i32 s48, s48, s49
	v_lshl_add_u32 v180, v142, 6, s48
	v_add_u32_e32 v175, 0x2000, v180
	global_load_dwordx4 v[182:185], v154, s[36:37]
	global_load_dwordx4 v[186:189], v154, s[36:37] offset:64
	global_load_dwordx4 v[190:193], v154, s[36:37] offset:512
	global_load_dwordx4 v[194:197], v154, s[36:37] offset:576
	global_load_dwordx4 v[198:201], v155, s[36:37]
	global_load_dwordx4 v[202:205], v155, s[36:37] offset:64
	global_load_dwordx4 v[206:209], v155, s[36:37] offset:512
	global_load_dwordx4 v[210:213], v155, s[36:37] offset:576
	global_load_dwordx4 v[214:217], v156, s[36:37]
	global_load_dwordx4 v[218:221], v156, s[36:37] offset:64
	global_load_dwordx4 v[222:225], v156, s[36:37] offset:512
	global_load_dwordx4 v[226:229], v156, s[36:37] offset:576
	global_load_dwordx4 v[230:233], v157, s[36:37]
	global_load_dwordx4 v[234:237], v157, s[36:37] offset:64
	global_load_dwordx4 v[238:241], v157, s[36:37] offset:512
	global_load_dwordx4 v[242:245], v157, s[36:37] offset:576
	s_waitcnt vmcnt(15)
	v_add_f32_e32 v124, v124, v182
	v_add_f32_e32 v125, v125, v183
	v_add_f32_e32 v126, v126, v184
	v_add_f32_e32 v127, v127, v185
	global_store_dwordx4 v154, v[124:127], s[30:31]
	v_cvt_pk_bf16_f32 v178, v124, v125
	v_cvt_pk_bf16_f32 v179, v126, v127
	global_store_dwordx2 v165, v[178:179], s[38:39]
	v_mul_f32_e32 v176, v125, v125
	v_mul_f32_e32 v177, v127, v127
	v_fmac_f32_e32 v176, v124, v124
	v_fmac_f32_e32 v177, v126, v126
	v_add_f32_e32 v246, v176, v177
	global_load_dwordx4 v[182:185], v158, s[36:37]
	s_waitcnt vmcnt(17)
	v_add_f32_e32 v120, v120, v186
	v_add_f32_e32 v121, v121, v187
	v_add_f32_e32 v122, v122, v188
	v_add_f32_e32 v123, v123, v189
	global_store_dwordx4 v154, v[120:123], s[30:31] offset:64
	v_cvt_pk_bf16_f32 v178, v120, v121
	v_cvt_pk_bf16_f32 v179, v122, v123
	global_store_dwordx2 v165, v[178:179], s[38:39] offset:32
	v_mul_f32_e32 v176, v121, v121
	v_mul_f32_e32 v177, v123, v123
	v_fmac_f32_e32 v176, v120, v120
	v_fmac_f32_e32 v177, v122, v122
	v_add_f32_e32 v176, v176, v177
	v_add_f32_e32 v246, v246, v176
	global_load_dwordx4 v[186:189], v158, s[36:37] offset:64
	s_waitcnt vmcnt(19)
	v_add_f32_e32 v116, v116, v190
	v_add_f32_e32 v117, v117, v191
	v_add_f32_e32 v118, v118, v192
	v_add_f32_e32 v119, v119, v193
	global_store_dwordx4 v154, v[116:119], s[30:31] offset:512
	v_cvt_pk_bf16_f32 v178, v116, v117
	v_cvt_pk_bf16_f32 v179, v118, v119
	global_store_dwordx2 v165, v[178:179], s[38:39] offset:256
	v_mul_f32_e32 v176, v117, v117
	v_mul_f32_e32 v177, v119, v119
	v_fmac_f32_e32 v176, v116, v116
	v_fmac_f32_e32 v177, v118, v118
	v_add_f32_e32 v176, v176, v177
	v_add_f32_e32 v246, v246, v176
	global_load_dwordx4 v[190:193], v158, s[36:37] offset:512
	s_waitcnt vmcnt(21)
	v_add_f32_e32 v112, v112, v194
	v_add_f32_e32 v113, v113, v195
	v_add_f32_e32 v114, v114, v196
	v_add_f32_e32 v115, v115, v197
	global_store_dwordx4 v154, v[112:115], s[30:31] offset:576
	v_cvt_pk_bf16_f32 v178, v112, v113
	v_cvt_pk_bf16_f32 v179, v114, v115
	global_store_dwordx2 v165, v[178:179], s[38:39] offset:288
	v_mul_f32_e32 v176, v113, v113
	v_mul_f32_e32 v177, v115, v115
	v_fmac_f32_e32 v176, v112, v112
	v_fmac_f32_e32 v177, v114, v114
	v_add_f32_e32 v176, v176, v177
	v_add_f32_e32 v246, v246, v176
	global_load_dwordx4 v[194:197], v158, s[36:37] offset:576
	s_waitcnt vmcnt(23)
	v_add_f32_e32 v108, v108, v198
	v_add_f32_e32 v109, v109, v199
	v_add_f32_e32 v110, v110, v200
	v_add_f32_e32 v111, v111, v201
	global_store_dwordx4 v155, v[108:111], s[30:31]
	v_cvt_pk_bf16_f32 v178, v108, v109
	v_cvt_pk_bf16_f32 v179, v110, v111
	global_store_dwordx2 v166, v[178:179], s[38:39]
	v_mul_f32_e32 v176, v109, v109
	v_mul_f32_e32 v177, v111, v111
	v_fmac_f32_e32 v176, v108, v108
	v_fmac_f32_e32 v177, v110, v110
	v_add_f32_e32 v247, v176, v177
	global_load_dwordx4 v[198:201], v159, s[36:37]
	s_waitcnt vmcnt(25)
	v_add_f32_e32 v104, v104, v202
	v_add_f32_e32 v105, v105, v203
	v_add_f32_e32 v106, v106, v204
	v_add_f32_e32 v107, v107, v205
	global_store_dwordx4 v155, v[104:107], s[30:31] offset:64
	v_cvt_pk_bf16_f32 v178, v104, v105
	v_cvt_pk_bf16_f32 v179, v106, v107
	global_store_dwordx2 v166, v[178:179], s[38:39] offset:32
	v_mul_f32_e32 v176, v105, v105
	v_mul_f32_e32 v177, v107, v107
	v_fmac_f32_e32 v176, v104, v104
	v_fmac_f32_e32 v177, v106, v106
	v_add_f32_e32 v176, v176, v177
	v_add_f32_e32 v247, v247, v176
	global_load_dwordx4 v[202:205], v159, s[36:37] offset:64
	s_waitcnt vmcnt(27)
	v_add_f32_e32 v100, v100, v206
	v_add_f32_e32 v101, v101, v207
	v_add_f32_e32 v102, v102, v208
	v_add_f32_e32 v103, v103, v209
	global_store_dwordx4 v155, v[100:103], s[30:31] offset:512
	v_cvt_pk_bf16_f32 v178, v100, v101
	v_cvt_pk_bf16_f32 v179, v102, v103
	global_store_dwordx2 v166, v[178:179], s[38:39] offset:256
	v_mul_f32_e32 v176, v101, v101
	v_mul_f32_e32 v177, v103, v103
	v_fmac_f32_e32 v176, v100, v100
	v_fmac_f32_e32 v177, v102, v102
	v_add_f32_e32 v176, v176, v177
	v_add_f32_e32 v247, v247, v176
	global_load_dwordx4 v[206:209], v159, s[36:37] offset:512
	s_waitcnt vmcnt(29)
	v_add_f32_e32 v96, v96, v210
	v_add_f32_e32 v97, v97, v211
	v_add_f32_e32 v98, v98, v212
	v_add_f32_e32 v99, v99, v213
	global_store_dwordx4 v155, v[96:99], s[30:31] offset:576
	v_cvt_pk_bf16_f32 v178, v96, v97
	v_cvt_pk_bf16_f32 v179, v98, v99
	global_store_dwordx2 v166, v[178:179], s[38:39] offset:288
	v_mul_f32_e32 v176, v97, v97
	v_mul_f32_e32 v177, v99, v99
	v_fmac_f32_e32 v176, v96, v96
	v_fmac_f32_e32 v177, v98, v98
	v_add_f32_e32 v176, v176, v177
	v_add_f32_e32 v247, v247, v176
	global_load_dwordx4 v[210:213], v159, s[36:37] offset:576
	s_waitcnt vmcnt(31)
	v_add_f32_e32 v92, v92, v214
	v_add_f32_e32 v93, v93, v215
	v_add_f32_e32 v94, v94, v216
	v_add_f32_e32 v95, v95, v217
	global_store_dwordx4 v156, v[92:95], s[30:31]
	v_cvt_pk_bf16_f32 v178, v92, v93
	v_cvt_pk_bf16_f32 v179, v94, v95
	global_store_dwordx2 v167, v[178:179], s[38:39]
	v_mul_f32_e32 v176, v93, v93
	v_mul_f32_e32 v177, v95, v95
	v_fmac_f32_e32 v176, v92, v92
	v_fmac_f32_e32 v177, v94, v94
	v_add_f32_e32 v248, v176, v177
	global_load_dwordx4 v[214:217], v160, s[36:37]
	s_waitcnt vmcnt(33)
	v_add_f32_e32 v88, v88, v218
	v_add_f32_e32 v89, v89, v219
	v_add_f32_e32 v90, v90, v220
	v_add_f32_e32 v91, v91, v221
	global_store_dwordx4 v156, v[88:91], s[30:31] offset:64
	v_cvt_pk_bf16_f32 v178, v88, v89
	v_cvt_pk_bf16_f32 v179, v90, v91
	global_store_dwordx2 v167, v[178:179], s[38:39] offset:32
	v_mul_f32_e32 v176, v89, v89
	v_mul_f32_e32 v177, v91, v91
	v_fmac_f32_e32 v176, v88, v88
	v_fmac_f32_e32 v177, v90, v90
	v_add_f32_e32 v176, v176, v177
	v_add_f32_e32 v248, v248, v176
	global_load_dwordx4 v[218:221], v160, s[36:37] offset:64
	s_waitcnt vmcnt(35)
	v_add_f32_e32 v84, v84, v222
	v_add_f32_e32 v85, v85, v223
	v_add_f32_e32 v86, v86, v224
	v_add_f32_e32 v87, v87, v225
	global_store_dwordx4 v156, v[84:87], s[30:31] offset:512
	v_cvt_pk_bf16_f32 v178, v84, v85
	v_cvt_pk_bf16_f32 v179, v86, v87
	global_store_dwordx2 v167, v[178:179], s[38:39] offset:256
	v_mul_f32_e32 v176, v85, v85
	v_mul_f32_e32 v177, v87, v87
	v_fmac_f32_e32 v176, v84, v84
	v_fmac_f32_e32 v177, v86, v86
	v_add_f32_e32 v176, v176, v177
	v_add_f32_e32 v248, v248, v176
	global_load_dwordx4 v[222:225], v160, s[36:37] offset:512
	s_waitcnt vmcnt(37)
	v_add_f32_e32 v80, v80, v226
	v_add_f32_e32 v81, v81, v227
	v_add_f32_e32 v82, v82, v228
	v_add_f32_e32 v83, v83, v229
	global_store_dwordx4 v156, v[80:83], s[30:31] offset:576
	v_cvt_pk_bf16_f32 v178, v80, v81
	v_cvt_pk_bf16_f32 v179, v82, v83
	global_store_dwordx2 v167, v[178:179], s[38:39] offset:288
	v_mul_f32_e32 v176, v81, v81
	v_mul_f32_e32 v177, v83, v83
	v_fmac_f32_e32 v176, v80, v80
	v_fmac_f32_e32 v177, v82, v82
	v_add_f32_e32 v176, v176, v177
	v_add_f32_e32 v248, v248, v176
	global_load_dwordx4 v[226:229], v160, s[36:37] offset:576
	s_waitcnt vmcnt(39)
	v_add_f32_e32 v76, v76, v230
	v_add_f32_e32 v77, v77, v231
	v_add_f32_e32 v78, v78, v232
	v_add_f32_e32 v79, v79, v233
	global_store_dwordx4 v157, v[76:79], s[30:31]
	v_cvt_pk_bf16_f32 v178, v76, v77
	v_cvt_pk_bf16_f32 v179, v78, v79
	global_store_dwordx2 v168, v[178:179], s[38:39]
	v_mul_f32_e32 v176, v77, v77
	v_mul_f32_e32 v177, v79, v79
	v_fmac_f32_e32 v176, v76, v76
	v_fmac_f32_e32 v177, v78, v78
	v_add_f32_e32 v249, v176, v177
	global_load_dwordx4 v[230:233], v161, s[36:37]
	s_waitcnt vmcnt(41)
	v_add_f32_e32 v72, v72, v234
	v_add_f32_e32 v73, v73, v235
	v_add_f32_e32 v74, v74, v236
	v_add_f32_e32 v75, v75, v237
	global_store_dwordx4 v157, v[72:75], s[30:31] offset:64
	v_cvt_pk_bf16_f32 v178, v72, v73
	v_cvt_pk_bf16_f32 v179, v74, v75
	global_store_dwordx2 v168, v[178:179], s[38:39] offset:32
	v_mul_f32_e32 v176, v73, v73
	v_mul_f32_e32 v177, v75, v75
	v_fmac_f32_e32 v176, v72, v72
	v_fmac_f32_e32 v177, v74, v74
	v_add_f32_e32 v176, v176, v177
	v_add_f32_e32 v249, v249, v176
	global_load_dwordx4 v[234:237], v161, s[36:37] offset:64
	s_waitcnt vmcnt(43)
	v_add_f32_e32 v68, v68, v238
	v_add_f32_e32 v69, v69, v239
	v_add_f32_e32 v70, v70, v240
	v_add_f32_e32 v71, v71, v241
	global_store_dwordx4 v157, v[68:71], s[30:31] offset:512
	v_cvt_pk_bf16_f32 v178, v68, v69
	v_cvt_pk_bf16_f32 v179, v70, v71
	global_store_dwordx2 v168, v[178:179], s[38:39] offset:256
	v_mul_f32_e32 v176, v69, v69
	v_mul_f32_e32 v177, v71, v71
	v_fmac_f32_e32 v176, v68, v68
	v_fmac_f32_e32 v177, v70, v70
	v_add_f32_e32 v176, v176, v177
	v_add_f32_e32 v249, v249, v176
	global_load_dwordx4 v[238:241], v161, s[36:37] offset:512
	s_waitcnt vmcnt(45)
	v_add_f32_e32 v64, v64, v242
	v_add_f32_e32 v65, v65, v243
	v_add_f32_e32 v66, v66, v244
	v_add_f32_e32 v67, v67, v245
	global_store_dwordx4 v157, v[64:67], s[30:31] offset:576
	v_cvt_pk_bf16_f32 v178, v64, v65
	v_cvt_pk_bf16_f32 v179, v66, v67
	global_store_dwordx2 v168, v[178:179], s[38:39] offset:288
	v_mul_f32_e32 v176, v65, v65
	v_mul_f32_e32 v177, v67, v67
	v_fmac_f32_e32 v176, v64, v64
	v_fmac_f32_e32 v177, v66, v66
	v_add_f32_e32 v176, v176, v177
	v_add_f32_e32 v249, v249, v176
	global_load_dwordx4 v[242:245], v161, s[36:37] offset:576
	s_waitcnt vmcnt(45)
	v_add_f32_e32 v60, v60, v182
	v_add_f32_e32 v61, v61, v183
	v_add_f32_e32 v62, v62, v184
	v_add_f32_e32 v63, v63, v185
	global_store_dwordx4 v158, v[60:63], s[30:31]
	v_cvt_pk_bf16_f32 v178, v60, v61
	v_cvt_pk_bf16_f32 v179, v62, v63
	global_store_dwordx2 v169, v[178:179], s[38:39]
	v_mul_f32_e32 v176, v61, v61
	v_mul_f32_e32 v177, v63, v63
	v_fmac_f32_e32 v176, v60, v60
	v_fmac_f32_e32 v177, v62, v62
	v_add_f32_e32 v250, v176, v177
	s_waitcnt vmcnt(44)
	v_add_f32_e32 v56, v56, v186
	v_add_f32_e32 v57, v57, v187
	v_add_f32_e32 v58, v58, v188
	v_add_f32_e32 v59, v59, v189
	global_store_dwordx4 v158, v[56:59], s[30:31] offset:64
	v_cvt_pk_bf16_f32 v178, v56, v57
	v_cvt_pk_bf16_f32 v179, v58, v59
	global_store_dwordx2 v169, v[178:179], s[38:39] offset:32
	v_mul_f32_e32 v176, v57, v57
	v_mul_f32_e32 v177, v59, v59
	v_fmac_f32_e32 v176, v56, v56
	v_fmac_f32_e32 v177, v58, v58
	v_add_f32_e32 v176, v176, v177
	v_add_f32_e32 v250, v250, v176
	s_waitcnt vmcnt(43)
	v_add_f32_e32 v52, v52, v190
	v_add_f32_e32 v53, v53, v191
	v_add_f32_e32 v54, v54, v192
	v_add_f32_e32 v55, v55, v193
	global_store_dwordx4 v158, v[52:55], s[30:31] offset:512
	v_cvt_pk_bf16_f32 v178, v52, v53
	v_cvt_pk_bf16_f32 v179, v54, v55
	global_store_dwordx2 v169, v[178:179], s[38:39] offset:256
	v_mul_f32_e32 v176, v53, v53
	v_mul_f32_e32 v177, v55, v55
	v_fmac_f32_e32 v176, v52, v52
	v_fmac_f32_e32 v177, v54, v54
	v_add_f32_e32 v176, v176, v177
	v_add_f32_e32 v250, v250, v176
	s_waitcnt vmcnt(42)
	v_add_f32_e32 v48, v48, v194
	v_add_f32_e32 v49, v49, v195
	v_add_f32_e32 v50, v50, v196
	v_add_f32_e32 v51, v51, v197
	global_store_dwordx4 v158, v[48:51], s[30:31] offset:576
	v_cvt_pk_bf16_f32 v178, v48, v49
	v_cvt_pk_bf16_f32 v179, v50, v51
	global_store_dwordx2 v169, v[178:179], s[38:39] offset:288
	v_mul_f32_e32 v176, v49, v49
	v_mul_f32_e32 v177, v51, v51
	v_fmac_f32_e32 v176, v48, v48
	v_fmac_f32_e32 v177, v50, v50
	v_add_f32_e32 v176, v176, v177
	v_add_f32_e32 v250, v250, v176
	s_waitcnt vmcnt(41)
	v_add_f32_e32 v44, v44, v198
	v_add_f32_e32 v45, v45, v199
	v_add_f32_e32 v46, v46, v200
	v_add_f32_e32 v47, v47, v201
	global_store_dwordx4 v159, v[44:47], s[30:31]
	v_cvt_pk_bf16_f32 v178, v44, v45
	v_cvt_pk_bf16_f32 v179, v46, v47
	global_store_dwordx2 v170, v[178:179], s[38:39]
	v_mul_f32_e32 v176, v45, v45
	v_mul_f32_e32 v177, v47, v47
	v_fmac_f32_e32 v176, v44, v44
	v_fmac_f32_e32 v177, v46, v46
	v_add_f32_e32 v251, v176, v177
	s_waitcnt vmcnt(40)
	v_add_f32_e32 v40, v40, v202
	v_add_f32_e32 v41, v41, v203
	v_add_f32_e32 v42, v42, v204
	v_add_f32_e32 v43, v43, v205
	global_store_dwordx4 v159, v[40:43], s[30:31] offset:64
	v_cvt_pk_bf16_f32 v178, v40, v41
	v_cvt_pk_bf16_f32 v179, v42, v43
	global_store_dwordx2 v170, v[178:179], s[38:39] offset:32
	v_mul_f32_e32 v176, v41, v41
	v_mul_f32_e32 v177, v43, v43
	v_fmac_f32_e32 v176, v40, v40
	v_fmac_f32_e32 v177, v42, v42
	v_add_f32_e32 v176, v176, v177
	v_add_f32_e32 v251, v251, v176
	s_waitcnt vmcnt(39)
	v_add_f32_e32 v36, v36, v206
	v_add_f32_e32 v37, v37, v207
	v_add_f32_e32 v38, v38, v208
	v_add_f32_e32 v39, v39, v209
	global_store_dwordx4 v159, v[36:39], s[30:31] offset:512
	v_cvt_pk_bf16_f32 v178, v36, v37
	v_cvt_pk_bf16_f32 v179, v38, v39
	global_store_dwordx2 v170, v[178:179], s[38:39] offset:256
	v_mul_f32_e32 v176, v37, v37
	v_mul_f32_e32 v177, v39, v39
	v_fmac_f32_e32 v176, v36, v36
	v_fmac_f32_e32 v177, v38, v38
	v_add_f32_e32 v176, v176, v177
	v_add_f32_e32 v251, v251, v176
	s_waitcnt vmcnt(38)
	v_add_f32_e32 v32, v32, v210
	v_add_f32_e32 v33, v33, v211
	v_add_f32_e32 v34, v34, v212
	v_add_f32_e32 v35, v35, v213
	global_store_dwordx4 v159, v[32:35], s[30:31] offset:576
	v_cvt_pk_bf16_f32 v178, v32, v33
	v_cvt_pk_bf16_f32 v179, v34, v35
	global_store_dwordx2 v170, v[178:179], s[38:39] offset:288
	v_mul_f32_e32 v176, v33, v33
	v_mul_f32_e32 v177, v35, v35
	v_fmac_f32_e32 v176, v32, v32
	v_fmac_f32_e32 v177, v34, v34
	v_add_f32_e32 v176, v176, v177
	v_add_f32_e32 v251, v251, v176
	s_waitcnt vmcnt(37)
	v_add_f32_e32 v28, v28, v214
	v_add_f32_e32 v29, v29, v215
	v_add_f32_e32 v30, v30, v216
	v_add_f32_e32 v31, v31, v217
	global_store_dwordx4 v160, v[28:31], s[30:31]
	v_cvt_pk_bf16_f32 v178, v28, v29
	v_cvt_pk_bf16_f32 v179, v30, v31
	global_store_dwordx2 v171, v[178:179], s[38:39]
	v_mul_f32_e32 v176, v29, v29
	v_mul_f32_e32 v177, v31, v31
	v_fmac_f32_e32 v176, v28, v28
	v_fmac_f32_e32 v177, v30, v30
	v_add_f32_e32 v252, v176, v177
	s_waitcnt vmcnt(36)
	v_add_f32_e32 v24, v24, v218
	v_add_f32_e32 v25, v25, v219
	v_add_f32_e32 v26, v26, v220
	v_add_f32_e32 v27, v27, v221
	global_store_dwordx4 v160, v[24:27], s[30:31] offset:64
	v_cvt_pk_bf16_f32 v178, v24, v25
	v_cvt_pk_bf16_f32 v179, v26, v27
	global_store_dwordx2 v171, v[178:179], s[38:39] offset:32
	v_mul_f32_e32 v176, v25, v25
	v_mul_f32_e32 v177, v27, v27
	v_fmac_f32_e32 v176, v24, v24
	v_fmac_f32_e32 v177, v26, v26
	v_add_f32_e32 v176, v176, v177
	v_add_f32_e32 v252, v252, v176
	s_waitcnt vmcnt(35)
	v_add_f32_e32 v20, v20, v222
	v_add_f32_e32 v21, v21, v223
	v_add_f32_e32 v22, v22, v224
	v_add_f32_e32 v23, v23, v225
	global_store_dwordx4 v160, v[20:23], s[30:31] offset:512
	v_cvt_pk_bf16_f32 v178, v20, v21
	v_cvt_pk_bf16_f32 v179, v22, v23
	global_store_dwordx2 v171, v[178:179], s[38:39] offset:256
	v_mul_f32_e32 v176, v21, v21
	v_mul_f32_e32 v177, v23, v23
	v_fmac_f32_e32 v176, v20, v20
	v_fmac_f32_e32 v177, v22, v22
	v_add_f32_e32 v176, v176, v177
	v_add_f32_e32 v252, v252, v176
	s_waitcnt vmcnt(34)
	v_add_f32_e32 v16, v16, v226
	v_add_f32_e32 v17, v17, v227
	v_add_f32_e32 v18, v18, v228
	v_add_f32_e32 v19, v19, v229
	global_store_dwordx4 v160, v[16:19], s[30:31] offset:576
	v_cvt_pk_bf16_f32 v178, v16, v17
	v_cvt_pk_bf16_f32 v179, v18, v19
	global_store_dwordx2 v171, v[178:179], s[38:39] offset:288
	v_mul_f32_e32 v176, v17, v17
	v_mul_f32_e32 v177, v19, v19
	v_fmac_f32_e32 v176, v16, v16
	v_fmac_f32_e32 v177, v18, v18
	v_add_f32_e32 v176, v176, v177
	v_add_f32_e32 v252, v252, v176
	s_waitcnt vmcnt(33)
	v_add_f32_e32 v12, v12, v230
	v_add_f32_e32 v13, v13, v231
	v_add_f32_e32 v14, v14, v232
	v_add_f32_e32 v15, v15, v233
	global_store_dwordx4 v161, v[12:15], s[30:31]
	v_cvt_pk_bf16_f32 v178, v12, v13
	v_cvt_pk_bf16_f32 v179, v14, v15
	global_store_dwordx2 v172, v[178:179], s[38:39]
	v_mul_f32_e32 v176, v13, v13
	v_mul_f32_e32 v177, v15, v15
	v_fmac_f32_e32 v176, v12, v12
	v_fmac_f32_e32 v177, v14, v14
	v_add_f32_e32 v253, v176, v177
	s_waitcnt vmcnt(32)
	v_add_f32_e32 v8, v8, v234
	v_add_f32_e32 v9, v9, v235
	v_add_f32_e32 v10, v10, v236
	v_add_f32_e32 v11, v11, v237
	global_store_dwordx4 v161, v[8:11], s[30:31] offset:64
	v_cvt_pk_bf16_f32 v178, v8, v9
	v_cvt_pk_bf16_f32 v179, v10, v11
	global_store_dwordx2 v172, v[178:179], s[38:39] offset:32
	v_mul_f32_e32 v176, v9, v9
	v_mul_f32_e32 v177, v11, v11
	v_fmac_f32_e32 v176, v8, v8
	v_fmac_f32_e32 v177, v10, v10
	v_add_f32_e32 v176, v176, v177
	v_add_f32_e32 v253, v253, v176
	s_waitcnt vmcnt(31)
	v_add_f32_e32 v4, v4, v238
	v_add_f32_e32 v5, v5, v239
	v_add_f32_e32 v6, v6, v240
	v_add_f32_e32 v7, v7, v241
	global_store_dwordx4 v161, v[4:7], s[30:31] offset:512
	v_cvt_pk_bf16_f32 v178, v4, v5
	v_cvt_pk_bf16_f32 v179, v6, v7
	global_store_dwordx2 v172, v[178:179], s[38:39] offset:256
	v_mul_f32_e32 v176, v5, v5
	v_mul_f32_e32 v177, v7, v7
	v_fmac_f32_e32 v176, v4, v4
	v_fmac_f32_e32 v177, v6, v6
	v_add_f32_e32 v176, v176, v177
	v_add_f32_e32 v253, v253, v176
	s_waitcnt vmcnt(30)
	v_add_f32_e32 v0, v0, v242
	v_add_f32_e32 v1, v1, v243
	v_add_f32_e32 v2, v2, v244
	v_add_f32_e32 v3, v3, v245
	global_store_dwordx4 v161, v[0:3], s[30:31] offset:576
	v_cvt_pk_bf16_f32 v178, v0, v1
	v_cvt_pk_bf16_f32 v179, v2, v3
	global_store_dwordx2 v172, v[178:179], s[38:39] offset:288
	v_mul_f32_e32 v176, v1, v1
	v_mul_f32_e32 v177, v3, v3
	v_fmac_f32_e32 v176, v0, v0
	v_fmac_f32_e32 v177, v2, v2
	v_add_f32_e32 v176, v176, v177
	v_add_f32_e32 v253, v253, v176
	ds_bpermute_b32 v182, v173, v246
	ds_bpermute_b32 v183, v173, v247
	ds_bpermute_b32 v184, v173, v248
	ds_bpermute_b32 v185, v173, v249
	ds_bpermute_b32 v186, v173, v250
	ds_bpermute_b32 v187, v173, v251
	ds_bpermute_b32 v188, v173, v252
	ds_bpermute_b32 v189, v173, v253
	s_waitcnt lgkmcnt(0)
	v_add_f32_e32 v246, v246, v182
	v_add_f32_e32 v247, v247, v183
	v_add_f32_e32 v248, v248, v184
	v_add_f32_e32 v249, v249, v185
	v_add_f32_e32 v250, v250, v186
	v_add_f32_e32 v251, v251, v187
	v_add_f32_e32 v252, v252, v188
	v_add_f32_e32 v253, v253, v189
	ds_bpermute_b32 v182, v174, v246
	ds_bpermute_b32 v183, v174, v247
	ds_bpermute_b32 v184, v174, v248
	ds_bpermute_b32 v185, v174, v249
	ds_bpermute_b32 v186, v174, v250
	ds_bpermute_b32 v187, v174, v251
	ds_bpermute_b32 v188, v174, v252
	ds_bpermute_b32 v189, v174, v253
	s_waitcnt lgkmcnt(0)
	v_add_f32_e32 v246, v246, v182
	v_add_f32_e32 v247, v247, v183
	v_add_f32_e32 v248, v248, v184
	v_add_f32_e32 v249, v249, v185
	v_add_f32_e32 v250, v250, v186
	v_add_f32_e32 v251, v251, v187
	v_add_f32_e32 v252, v252, v188
	v_add_f32_e32 v253, v253, v189
	s_and_saveexec_b64 s[50:51], s[6:7]
	global_store_dword v180, v246, s[40:41]
	global_store_dword v180, v247, s[40:41] offset:1024
	global_store_dword v180, v248, s[40:41] offset:2048
	global_store_dword v180, v249, s[40:41] offset:3072
	global_store_dword v175, v250, s[40:41]
	global_store_dword v175, v251, s[40:41] offset:1024
	global_store_dword v175, v252, s[40:41] offset:2048
	global_store_dword v175, v253, s[40:41] offset:3072
